# v20 + in-projection column tiles visited in rotated order (z_s, q, k, v, z_a, u): the u segment that S5 reads first is produced last
# baseline (speedup 1.0000x reference)
; #define PHASE_BEGIN() int zp_ = 0; asm volatile("" : "+v"(zp_)); int wv_ = wave_s, bxp_ = bx; asm volatile("" : "+s"(wv_), "+s"(bxp_)); const int lane = (int)__builtin_amdgcn_mbcnt_hi(~0u, __builtin_amdgcn_mbcnt_lo(~0u, (unsigned)zp_)), wave = wv_; const int tidp = wv_ * 64 + lane; const int gw = bxp_ * NWAVES + wave; unsigned char* ws = (unsigned char*)ldp(L, 25); (void)lane; (void)gw
;     __host__ __device__ bool next(int i, Unit& u) const {
;         const long L = (long)i * G + c; if (L >= nwg) return false;
;         int wgid = (int)L; { const int q = nwg / NXCD, r = nwg % NXCD, xcd = wgid % NXCD, off = wgid / NXCD; wgid = (xcd < r ? xcd * (q + 1) : r * (q + 1) + (xcd - r) * q) + off; }
;         const int nig = WGM * nN, gid = wgid / nig, fm = gid * WGM, gsz = (nM - fm) < WGM ? (nM - fm) : WGM;
;         u.pm = fm + ((wgid % nig) % gsz); u.pn = (wgid % nig) / gsz; return true;
;     }
; __global__ void __launch_bounds__(NWAVES * 64, 2) fwd_kernel(Args args) {
;     ...
;     for (int l = 0; l < DEPTH; ++l) {
;         {
;             PHASE_BEGIN();
;             pg8::Gemm g{WSP(const bf16, WS_H), WSP(const bf16, WS_WIN) + (size_t)l * 6144 * 2048, NTOK, INW, 2048, 2048, 2048, 1 << 30, 0};
;             pg8::StaticOrder S; S.init(NTOK, INW, G, bx);
;             pg8::EpiInProj Ep{ws, l};
;             pg8::gemm_phase<pg8::EpiInProj, pg8::StaticOrder, true, true>(L, g, S, Ep, tidp);
.LBB0_163:
	v_writelane_b32 v255, s48, 4
	s_nop 1
	v_writelane_b32 v255, s49, 5
	s_or_b64 exec, exec, s[36:37]
	s_cmpk_lt_i32 s2, 0xc00
	s_mul_i32 s0, s45, s44
	s_cselect_b64 s[4:5], -1, 0
	s_ashr_i32 s45, s2, 31
	s_lshr_b32 s1, s45, 29
	s_add_i32 s1, s2, s1
	s_ashr_i32 s6, s1, 3
	s_and_b32 s1, s1, -8
	s_sub_i32 s1, s2, s1
	s_ashr_i32 s3, s44, 31
	v_writelane_b32 v255, s4, 6
	s_cmpk_lt_i32 s2, 0x200
	s_movk_i32 s11, 0x181
	v_writelane_b32 v255, s5, 7
	s_cselect_b64 s[4:5], -1, 0
	v_writelane_b32 v255, s4, 8
	s_mul_i32 s10, s0, s10
	s_mul_i32 s0, s1, 0x41
	v_writelane_b32 v255, s5, 9
	s_lshl_b32 s4, s1, 6
	s_cmpk_lt_i32 s2, 0x400
	s_cselect_b64 s[8:9], -1, 0
	s_ashr_i32 s7, s44, 3
	v_writelane_b32 v255, s8, 10
	s_mul_i32 s7, s7, s1
	s_lshl_b32 s5, s1, 7
	v_writelane_b32 v255, s9, 11
	s_and_b32 s8, s44, 7
	s_add_i32 s9, s7, s6
	s_cmp_lt_i32 s1, 0
	s_cselect_b32 s11, s11, 0x180
	s_mul_i32 s7, s1, 0x81
	s_mul_i32 s1, s1, s11
	s_cselect_b32 s4, s0, s4
	s_cselect_b32 s7, s7, s5
	s_add_i32 s1, s1, s6
	s_mul_hi_i32 s0, s1, 0x2aaaaaab
	s_lshr_b32 s5, s0, 31
	s_ashr_i32 s0, s0, 5
	s_add_i32 s0, s0, s5
	s_mul_i32 s5, s0, 0xc0
	s_sub_i32 s1, s1, s5
	s_lshl_b32 s11, s0, 3
	s_bfe_u32 s0, s1, 0x3001c
	s_add_i32 s5, s1, s0
	s_sext_i32_i16 s12, s5
	s_and_b32 s5, s5, 0xfff8
	s_sub_i32 s1, s1, s5
	s_sext_i32_i16 s1, s1
	s_lshr_b32 s0, s12, 3
	s_add_i32 s14, s11, s1
	s_ashr_i32 s1, s12, 3
	s_add_i32 s1, s1, 4
	s_cmp_ge_u32 s1, 24
	s_cselect_b32 s0, 24, 0
	s_sub_i32 s1, s1, s0
	s_mov_b32 s0, s1
	s_add_i32 s12, s4, s6
	v_writelane_b32 v255, s1, 12
	s_ashr_i32 s1, s12, 31
	s_lshr_b32 s1, s1, 29
	s_add_i32 s1, s12, s1
	s_ashr_i32 s4, s1, 3
	s_ashr_i32 s5, s4, 31
	s_add_i32 s1, s7, s6
	s_lshl_b64 s[16:17], s[4:5], 16
	s_ashr_i32 s5, s1, 31
	s_lshr_b32 s5, s5, 26
	s_add_i32 s5, s1, s5
	s_ashr_i32 s6, s5, 6
	s_and_b32 s5, s5, 0xffc0
	s_sub_i32 s1, s1, s5
	s_bfe_i32 s5, s1, 0x80000
	s_bfe_u32 s5, s5, 0x3000c
	s_add_i32 s5, s1, s5
	s_lshl_b32 s7, s6, 3
	s_bfe_i32 s6, s5, 0x80000
	s_and_b32 s5, s5, 0xf8
	s_sub_i32 s1, s1, s5
	v_writelane_b32 v255, s16, 13
	s_sext_i32_i8 s1, s1
	s_sext_i32_i16 s11, s6
	v_writelane_b32 v255, s17, 14
	s_add_i32 s16, s7, s1
	s_ashr_i32 s1, s11, 3
	s_ashr_i32 s17, s16, 31
	s_lshr_b32 s6, s11, 3
	v_writelane_b32 v255, s1, 15
	s_lshl_b64 s[18:19], s[16:17], 19
	v_writelane_b32 v255, s18, 16
	s_bfe_i64 s[6:7], s[6:7], 0x100000
	s_mul_hi_i32 s1, s12, 0x30000
	v_writelane_b32 v255, s19, 17
	s_lshl_b64 s[18:19], s[6:7], 19
	v_writelane_b32 v255, s18, 18
	s_cmp_eq_u32 s8, 0
	s_cselect_b32 s5, s9, s2
	v_writelane_b32 v255, s19, 19
	v_writelane_b32 v255, s1, 20
	v_writelane_b32 v255, s12, 21
	s_mul_i32 s1, s12, 0x30000
	v_writelane_b32 v255, s1, 22
	s_mul_hi_i32 s1, s4, 0x30000
	v_writelane_b32 v255, s1, 23
	s_mul_i32 s1, s4, 0x30000
	s_cmpk_lt_i32 s5, 0x100
	v_writelane_b32 v255, s1, 24
	s_cselect_b64 s[8:9], -1, 0
	v_writelane_b32 v255, s8, 25
	s_mov_b32 s4, s14
	s_ashr_i32 s15, s14, 31
	v_writelane_b32 v255, s9, 26
	v_writelane_b32 v255, s4, 27
	s_lshl_b64 s[8:9], s[14:15], 20
	s_bfe_i64 s[0:1], s[0:1], 0x100000
	v_writelane_b32 v255, s5, 28
	v_writelane_b32 v255, s8, 29
	s_lshl_b64 s[0:1], s[0:1], 20
	s_mov_b32 s51, 0
	v_writelane_b32 v255, s9, 30
	v_writelane_b32 v255, s0, 31
	v_cvt_f32_u32_e32 v0, s52
	s_mov_b32 s53, s52
	v_writelane_b32 v255, s1, 32
	s_mov_b32 s1, -1
	s_mov_b32 s0, s51
	s_and_b64 s[0:1], s[52:53], s[0:1]
	v_writelane_b32 v255, s0, 33
	v_rcp_iflag_f32_e32 v0, v0
	v_mov_b32_e32 v205, 0
	v_writelane_b32 v255, s1, 34
	s_lshl_b32 s0, s44, 10
	v_writelane_b32 v255, s0, 35
	v_writelane_b32 v255, s0, 36
	s_mov_b32 s0, s16
	v_writelane_b32 v255, s0, 37
	v_mul_f32_e32 v0, 0x4f7ffffe, v0
	v_cvt_u32_f32_e32 v0, v0
	v_writelane_b32 v255, s1, 38
	s_lshl_b64 s[0:1], s[16:17], 20
	v_writelane_b32 v255, s0, 39
	s_mov_b32 s79, 0xffff0000
	v_mov_b32_e32 v231, 0x358637bd
	v_writelane_b32 v255, s1, 40
	s_lshl_b64 s[0:1], s[6:7], 20
	v_writelane_b32 v255, s0, 41
	s_movk_i32 s33, 0x300
	s_mov_b32 s11, 0x25a00000
	v_writelane_b32 v255, s1, 42
	s_sub_i32 s0, 0, s52
	v_mul_lo_u32 v1, s0, v0
	s_add_u32 s0, s2, s44
	s_addc_u32 s1, s45, s3
	v_writelane_b32 v255, s0, 43
	v_mul_hi_u32 v1, v0, v1
	s_ashr_i32 s53, s52, 31
	v_writelane_b32 v255, s1, 44
	v_writelane_b32 v255, s5, 45
	s_lshl_b32 s0, s5, 5
	v_writelane_b32 v255, s0, 46
	s_add_i32 s0, 0, 0x20200
	v_writelane_b32 v255, s0, 47
	s_add_i32 s0, 0, 0x20204
	v_writelane_b32 v255, s0, 48
	s_mov_b32 s0, s52
	v_writelane_b32 v255, s0, 49
	v_add_u32_e32 v230, v0, v1
	s_lshl_b32 s78, s44, 5
	v_mov_b32_e32 v254, 1
	s_movk_i32 s90, 0x7fff
	s_mov_b32 s91, 0x3fb8aa3b
	s_mov_b32 s40, 0xc2ce8ed0
	s_mov_b32 s41, 0x42b17218
	s_mov_b32 s86, 0x15a00000
	s_mov_b32 s87, 0x41000000
	v_mov_b32_e32 v234, 0x260
	v_mov_b32_e32 v235, 0x3e38aa3b
	v_mov_b64_e32 v[232:233], 0x200
	v_mov_b64_e32 v[212:213], 0x1ff
	v_mov_b32_e32 v236, 0x7f800000
	v_mov_b32_e32 v237, 0xff800000
	s_mov_b32 s38, 0xf800000
	s_mov_b32 s4, 0
	v_writelane_b32 v255, s1, 50
	s_lshl_b64 s[42:43], s[52:53], 2
	s_mov_b64 s[80:81], 0xda00000
	s_mov_b64 s[82:83], 0x80
	s_mov_b64 s[84:85], 0x100
	s_mov_b64 s[88:89], 0x40000
	s_mov_b64 s[92:93], 0x200
	s_mov_b64 s[94:95], 0x180
	s_mov_b64 s[96:97], 0x280
	s_mov_b64 s[68:69], 0x29a80000
	s_mov_b64 s[52:53], 0x2da40000
	s_waitcnt lgkmcnt(0)
	s_barrier
	s_branch .LBB0_166

; template <class Epi, class Sched, bool ALIGN_EPI = false, bool SP2 = false>
; __device__ __forceinline__ void gemm_phase(PG8_LAS unsigned char* lds, const Gemm g, const Sched& S, const Epi& E, const int tid) {
;     ...
;         const bool has_next = S.next(ui + 1, nxt);
;         const char* nA = has_next ? (const char*)g.A + (size_t)nxt.pm * 2 * hstepA : cA; const char* nB = has_next ? (const char*)g.Bt + ((size_t)(nxt.pm / g.grp_tiles) * g.grp_brows + (size_t)nxt.pn * BM) * g.ldb * 2 : cB;
;     ...
; #pragma unroll
;         for (int a = 0; a < 2; ++a)
; #pragma unroll
;             for (int b = 0; b < 2; ++b)
; #pragma unroll
;                 for (int m = 0; m < 4; ++m)
; #pragma unroll
;                     for (int n = 0; n < 2; ++n) acc[a][b][m][n] = (f32x4){0.f, 0.f, 0.f, 0.f};
;         cur = nxt; cA = nA; cB = nB; ++ui;
.LBB0_174:
	s_add_i32 s14, s14, 4
	s_cmp_ge_u32 s14, 24
	s_cselect_b32 s72, 24, 0
	s_sub_i32 s14, s14, s72
	s_ashr_i32 s17, s16, 31
	s_lshl_b64 s[18:19], s[16:17], 20
	s_add_u32 s18, s30, s18
	s_addc_u32 s19, s31, s19
	s_and_b64 s[20:21], s[4:5], exec
	s_cselect_b32 s17, s19, s23
	s_cselect_b32 s27, s18, s22
	s_ashr_i32 s15, s14, 31
	s_lshl_b64 s[20:21], s[14:15], 20
	s_add_u32 s20, s34, s20
	s_addc_u32 s21, s35, s21
	s_and_b64 s[24:25], s[4:5], exec
	s_cselect_b32 s15, s21, s7
	s_cselect_b32 s28, s20, s6
	s_add_u32 s29, s6, 0x100
	s_addc_u32 s43, s7, 0
	s_add_u32 s6, s22, 0x80080
	v_mov_b32_e32 v12, 0
	s_addc_u32 s7, s23, 0
	s_mov_b32 s59, -2
	v_mov_b32_e32 v13, v12
	v_mov_b32_e32 v14, v12
	v_mov_b32_e32 v15, v12
	v_mov_b32_e32 v8, v12
	v_mov_b32_e32 v9, v12
	v_mov_b32_e32 v10, v12
	v_mov_b32_e32 v11, v12
	v_mov_b32_e32 v40, v12
	v_mov_b32_e32 v41, v12
	v_mov_b32_e32 v42, v12
	v_mov_b32_e32 v43, v12
	v_mov_b32_e32 v56, v12
	v_mov_b32_e32 v57, v12
	v_mov_b32_e32 v58, v12
	v_mov_b32_e32 v59, v12
	v_mov_b32_e32 v88, v12
	v_mov_b32_e32 v89, v12
	v_mov_b32_e32 v90, v12
	v_mov_b32_e32 v91, v12
	v_mov_b32_e32 v92, v12
	v_mov_b32_e32 v93, v12
	v_mov_b32_e32 v94, v12
	v_mov_b32_e32 v95, v12
	v_mov_b32_e32 v104, v12
	v_mov_b32_e32 v105, v12
	v_mov_b32_e32 v106, v12
	v_mov_b32_e32 v107, v12
	v_mov_b32_e32 v108, v12
	v_mov_b32_e32 v109, v12
	v_mov_b32_e32 v110, v12
	v_mov_b32_e32 v111, v12
	v_mov_b32_e32 v4, v12
	v_mov_b32_e32 v5, v12
	v_mov_b32_e32 v6, v12
	v_mov_b32_e32 v7, v12
	v_mov_b32_e32 v0, v12
	v_mov_b32_e32 v1, v12
	v_mov_b32_e32 v2, v12
	v_mov_b32_e32 v3, v12
	v_mov_b32_e32 v20, v12
	v_mov_b32_e32 v21, v12
	v_mov_b32_e32 v22, v12
	v_mov_b32_e32 v23, v12
	v_mov_b32_e32 v16, v12
	v_mov_b32_e32 v17, v12
	v_mov_b32_e32 v18, v12
	v_mov_b32_e32 v19, v12
	v_mov_b32_e32 v80, v12
	v_mov_b32_e32 v81, v12
	v_mov_b32_e32 v82, v12
	v_mov_b32_e32 v83, v12
	v_mov_b32_e32 v72, v12
	v_mov_b32_e32 v73, v12
	v_mov_b32_e32 v74, v12
	v_mov_b32_e32 v75, v12
	v_mov_b32_e32 v100, v12
	v_mov_b32_e32 v101, v12
	v_mov_b32_e32 v102, v12
	v_mov_b32_e32 v103, v12
	v_mov_b32_e32 v96, v12
	v_mov_b32_e32 v97, v12
	v_mov_b32_e32 v98, v12
	v_mov_b32_e32 v99, v12
	v_mov_b32_e32 v28, v12
	v_mov_b32_e32 v29, v12
	v_mov_b32_e32 v30, v12
	v_mov_b32_e32 v31, v12
	v_mov_b32_e32 v44, v12
	v_mov_b32_e32 v45, v12
	v_mov_b32_e32 v46, v12
	v_mov_b32_e32 v47, v12
	v_mov_b32_e32 v48, v12
	v_mov_b32_e32 v49, v12
	v_mov_b32_e32 v50, v12
	v_mov_b32_e32 v51, v12
	v_mov_b32_e32 v64, v12
	v_mov_b32_e32 v65, v12
	v_mov_b32_e32 v66, v12
	v_mov_b32_e32 v67, v12
	v_mov_b32_e32 v68, v12
	v_mov_b32_e32 v69, v12
	v_mov_b32_e32 v70, v12
	v_mov_b32_e32 v71, v12
	v_mov_b32_e32 v84, v12
	v_mov_b32_e32 v85, v12
	v_mov_b32_e32 v86, v12
	v_mov_b32_e32 v87, v12
	v_mov_b32_e32 v116, v12
	v_mov_b32_e32 v117, v12
	v_mov_b32_e32 v118, v12
	v_mov_b32_e32 v119, v12
	v_mov_b32_e32 v124, v12
	v_mov_b32_e32 v125, v12
	v_mov_b32_e32 v126, v12
	v_mov_b32_e32 v127, v12
	v_mov_b32_e32 v24, v12
	v_mov_b32_e32 v25, v12
	v_mov_b32_e32 v26, v12
	v_mov_b32_e32 v27, v12
	v_mov_b32_e32 v32, v12
	v_mov_b32_e32 v33, v12
	v_mov_b32_e32 v34, v12
	v_mov_b32_e32 v35, v12
	v_mov_b32_e32 v36, v12
	v_mov_b32_e32 v37, v12
	v_mov_b32_e32 v38, v12
	v_mov_b32_e32 v39, v12
	v_mov_b32_e32 v52, v12
	v_mov_b32_e32 v53, v12
	v_mov_b32_e32 v54, v12
	v_mov_b32_e32 v55, v12
	v_mov_b32_e32 v60, v12
	v_mov_b32_e32 v61, v12
	v_mov_b32_e32 v62, v12
	v_mov_b32_e32 v63, v12
	v_mov_b32_e32 v76, v12
	v_mov_b32_e32 v77, v12
	v_mov_b32_e32 v78, v12
	v_mov_b32_e32 v79, v12
	v_mov_b32_e32 v112, v12
	v_mov_b32_e32 v113, v12
	v_mov_b32_e32 v114, v12
	v_mov_b32_e32 v115, v12
	v_mov_b32_e32 v120, v12
	v_mov_b32_e32 v121, v12
	v_mov_b32_e32 v122, v12
	v_mov_b32_e32 v123, v12
